# G1/G7 swiglu epilogue: hoist the 8 rstd loads, counted vmcnt(7) instead of vmcnt(0) ladder
# baseline (speedup 1.0000x reference)
; __device__ __forceinline__ unsigned cvt_pk_bf16(float lo, float hi) { f32x2_t v = {lo, hi}; bf16x2_t b = __builtin_convertvector(v, bf16x2_t); return __builtin_bit_cast(unsigned, b); }
; __device__ __forceinline__ float rstd_of(const float* ss, int row) { return __builtin_amdgcn_rsqf(ss[row] * (1.0f / 1024.0f) + RMS_EPS); }
; __device__ __forceinline__ float sigmoidf_(float v) { return __builtin_amdgcn_rcpf(1.0f + __builtin_amdgcn_exp2f(-v * LOG2E)); }
;     __device__ __forceinline__ void operator()(const Acc& acc, const Unit& u, int wr, int wc, int fr, int fq) const {
;         const int row0 = u.pm * BM + wr * 64 + fr, col0 = u.pn * 128 + wc * 32 + 8 * fq;
; #pragma unroll
;         for (int ai = 0; ai < 2; ++ai)
; #pragma unroll
;             for (int m = 0; m < 4; ++m) {
;                 const int row = row0 + ai * HALF + m * 16; const float rs = rstd_of(ss, row);
;                 float o[8];
; #pragma unroll
;                 for (int n = 0; n < 2; ++n)
; #pragma unroll
;                     for (int e = 0; e < 4; ++e) { const float gv = acc[ai][0][m][n][e] * rs, uv = acc[ai][1][m][n][e] * rs; o[4 * n + e] = gv * sigmoidf_(gv) * uv; }
;                 u32x4 w; w.x = cvt_pk_bf16(o[0], o[1]); w.y = cvt_pk_bf16(o[2], o[3]); w.z = cvt_pk_bf16(o[4], o[5]); w.w = cvt_pk_bf16(o[6], o[7]);
;                 *(u32x4*)(H + (size_t)row * FF + col0) = w;
.LBB0_217:
	v_lshl_add_u32 v144, s46, 8, v152
	v_ashrrev_i32_e32 v145, 31, v144
	v_lshl_add_u64 v[150:151], v[144:145], 2, s[48:49]
	global_load_dword v228, v[150:151], off
	global_load_dword v229, v[150:151], off offset:64
	global_load_dword v230, v[150:151], off offset:128
	global_load_dword v231, v[150:151], off offset:192
	global_load_dword v232, v[150:151], off offset:512
	global_load_dword v233, v[150:151], off offset:576
	global_load_dword v234, v[150:151], off offset:640
	global_load_dword v235, v[150:151], off offset:704
	v_lshl_or_b32 v148, s34, 7, v154
	v_mov_b64_e32 v[146:147], s[20:21]
	v_ashrrev_i32_e32 v149, 31, v148
	v_mad_i64_i32 v[164:165], s[6:7], v144, s33, v[146:147]
	v_lshlrev_b64 v[148:149], 1, v[148:149]
	v_lshl_add_u64 v[164:165], v[164:165], 0, v[148:149]
	s_andn2_b64 vcc, exec, s[4:5]
	s_mov_b64 s[4:5], -1
	s_waitcnt vmcnt(7)
	v_fmamk_f32 v145, v228, 0x3a800000, v158
	v_rsq_f32_e32 v162, v145
	s_nop 0
	v_pk_mul_f32 v[124:125], v[124:125], v[162:163] op_sel_hi:[1,0]
	v_pk_mul_f32 v[126:127], v[126:127], v[162:163] op_sel_hi:[1,0]
	v_pk_mul_f32 v[120:121], v[120:121], v[162:163] op_sel_hi:[1,0]
	v_pk_mul_f32 v[122:123], v[122:123], v[162:163] op_sel_hi:[1,0]
	v_pk_mul_f32 v[116:117], v[116:117], v[162:163] op_sel_hi:[1,0]
	v_pk_mul_f32 v[118:119], v[118:119], v[162:163] op_sel_hi:[1,0]
	v_pk_mul_f32 v[112:113], v[112:113], v[162:163] op_sel_hi:[1,0]
	v_pk_mul_f32 v[114:115], v[114:115], v[162:163] op_sel_hi:[1,0]
	v_mul_f32_e32 v145, 0xbfb8aa3b, v124
	v_mul_f32_e32 v159, 0xbfb8aa3b, v125
	v_mul_f32_e32 v162, 0xbfb8aa3b, v126
	v_mul_f32_e32 v163, 0xbfb8aa3b, v127
	v_mul_f32_e32 v166, 0xbfb8aa3b, v120
	v_mul_f32_e32 v167, 0xbfb8aa3b, v121
	v_mul_f32_e32 v168, 0xbfb8aa3b, v122
	v_mul_f32_e32 v169, 0xbfb8aa3b, v123
	v_exp_f32_e32 v145, v145
	v_exp_f32_e32 v159, v159
	v_exp_f32_e32 v162, v162
	v_exp_f32_e32 v163, v163
	v_exp_f32_e32 v166, v166
	v_exp_f32_e32 v167, v167
	v_exp_f32_e32 v168, v168
	v_exp_f32_e32 v169, v169
	v_add_f32_e32 v145, 1.0, v145
	v_add_f32_e32 v159, 1.0, v159
	v_add_f32_e32 v170, 1.0, v162
	v_add_f32_e32 v171, 1.0, v163
	v_add_f32_e32 v173, 1.0, v166
	v_add_f32_e32 v174, 1.0, v167
	v_add_f32_e32 v178, 1.0, v168
	v_add_f32_e32 v179, 1.0, v169
	v_rcp_f32_e32 v162, v145
	v_rcp_f32_e32 v163, v159
	v_rcp_f32_e32 v166, v170
	v_rcp_f32_e32 v167, v171
	v_rcp_f32_e32 v168, v173
	v_rcp_f32_e32 v169, v174
	v_rcp_f32_e32 v170, v178
	v_rcp_f32_e32 v171, v179
	v_pk_mul_f32 v[124:125], v[124:125], v[162:163]
	v_pk_mul_f32 v[126:127], v[126:127], v[166:167]
	v_pk_mul_f32 v[120:121], v[120:121], v[168:169]
	v_pk_mul_f32 v[122:123], v[122:123], v[170:171]
	v_pk_mul_f32 v[116:117], v[116:117], v[124:125]
	v_pk_mul_f32 v[118:119], v[118:119], v[126:127]
	v_pk_mul_f32 v[120:121], v[112:113], v[120:121]
	v_pk_mul_f32 v[122:123], v[114:115], v[122:123]
	v_cvt_pk_bf16_f32 v112, v116, v117
	v_cvt_pk_bf16_f32 v113, v118, v119
	v_cvt_pk_bf16_f32 v114, v120, v121
	v_cvt_pk_bf16_f32 v115, v122, v123
	global_store_dwordx4 v[164:165], v[112:115], off
	s_nop 0
	s_nop 0
	v_or_b32_e32 v113, 16, v144
	v_mad_i64_i32 v[114:115], s[6:7], v113, s33, v[146:147]
	v_lshl_add_u64 v[114:115], v[114:115], 0, v[148:149]
	s_waitcnt vmcnt(7)
	v_fmamk_f32 v112, v229, 0x3a800000, v158
	v_rsq_f32_e32 v112, v112
	s_nop 0
	v_pk_mul_f32 v[108:109], v[108:109], v[112:113] op_sel_hi:[1,0]
	v_pk_mul_f32 v[110:111], v[110:111], v[112:113] op_sel_hi:[1,0]
	v_pk_mul_f32 v[104:105], v[104:105], v[112:113] op_sel_hi:[1,0]
	v_pk_mul_f32 v[106:107], v[106:107], v[112:113] op_sel_hi:[1,0]
	v_pk_mul_f32 v[100:101], v[100:101], v[112:113] op_sel_hi:[1,0]
	v_pk_mul_f32 v[102:103], v[102:103], v[112:113] op_sel_hi:[1,0]
	v_pk_mul_f32 v[96:97], v[96:97], v[112:113] op_sel_hi:[1,0]
	v_pk_mul_f32 v[98:99], v[98:99], v[112:113] op_sel_hi:[1,0]
	v_mul_f32_e32 v112, 0xbfb8aa3b, v108
	v_mul_f32_e32 v113, 0xbfb8aa3b, v109
	v_mul_f32_e32 v116, 0xbfb8aa3b, v110
	v_mul_f32_e32 v117, 0xbfb8aa3b, v111
	v_mul_f32_e32 v118, 0xbfb8aa3b, v104
	v_mul_f32_e32 v119, 0xbfb8aa3b, v105
	v_mul_f32_e32 v120, 0xbfb8aa3b, v106
	v_mul_f32_e32 v121, 0xbfb8aa3b, v107
	v_exp_f32_e32 v112, v112
	v_exp_f32_e32 v113, v113
	v_exp_f32_e32 v116, v116
	v_exp_f32_e32 v117, v117
	v_exp_f32_e32 v118, v118
	v_exp_f32_e32 v119, v119
	v_exp_f32_e32 v120, v120
	v_exp_f32_e32 v121, v121
	v_add_f32_e32 v112, 1.0, v112
	v_add_f32_e32 v113, 1.0, v113
	v_add_f32_e32 v116, 1.0, v116
	v_add_f32_e32 v117, 1.0, v117
	v_add_f32_e32 v118, 1.0, v118
	v_add_f32_e32 v119, 1.0, v119
	v_add_f32_e32 v120, 1.0, v120
	v_add_f32_e32 v121, 1.0, v121
	v_rcp_f32_e32 v112, v112
	v_rcp_f32_e32 v113, v113
	v_rcp_f32_e32 v116, v116
	v_rcp_f32_e32 v117, v117
	v_rcp_f32_e32 v118, v118
	v_rcp_f32_e32 v119, v119
	v_rcp_f32_e32 v120, v120
	v_rcp_f32_e32 v121, v121
	v_pk_mul_f32 v[108:109], v[108:109], v[112:113]
	v_pk_mul_f32 v[110:111], v[110:111], v[116:117]
	v_pk_mul_f32 v[104:105], v[104:105], v[118:119]
	v_pk_mul_f32 v[106:107], v[106:107], v[120:121]
	v_pk_mul_f32 v[100:101], v[100:101], v[108:109]
	v_pk_mul_f32 v[102:103], v[102:103], v[110:111]
	v_pk_mul_f32 v[104:105], v[96:97], v[104:105]
	v_pk_mul_f32 v[106:107], v[98:99], v[106:107]
	v_cvt_pk_bf16_f32 v96, v100, v101
	v_cvt_pk_bf16_f32 v97, v102, v103
	v_cvt_pk_bf16_f32 v98, v104, v105
	v_cvt_pk_bf16_f32 v99, v106, v107
	global_store_dwordx4 v[114:115], v[96:99], off
	s_nop 0
	s_nop 0
	v_or_b32_e32 v97, 32, v144
	v_mad_i64_i32 v[98:99], s[6:7], v97, s33, v[146:147]
	v_lshl_add_u64 v[98:99], v[98:99], 0, v[148:149]
	s_waitcnt vmcnt(7)
; __device__ __forceinline__ unsigned cvt_pk_bf16(float lo, float hi) { f32x2_t v = {lo, hi}; bf16x2_t b = __builtin_convertvector(v, bf16x2_t); return __builtin_bit_cast(unsigned, b); }
; __device__ __forceinline__ float rstd_of(const float* ss, int row) { return __builtin_amdgcn_rsqf(ss[row] * (1.0f / 1024.0f) + RMS_EPS); }
; __device__ __forceinline__ float sigmoidf_(float v) { return __builtin_amdgcn_rcpf(1.0f + __builtin_amdgcn_exp2f(-v * LOG2E)); }
;     __device__ __forceinline__ void operator()(const Acc& acc, const Unit& u, int wr, int wc, int fr, int fq) const {
;     ...
;             for (int m = 0; m < 4; ++m) {
;                 const int row = row0 + ai * HALF + m * 16; const float rs = rstd_of(ss, row);
;                 float o[8];
; #pragma unroll
;                 for (int n = 0; n < 2; ++n)
; #pragma unroll
;                     for (int e = 0; e < 4; ++e) { const float gv = acc[ai][0][m][n][e] * rs, uv = acc[ai][1][m][n][e] * rs; o[4 * n + e] = gv * sigmoidf_(gv) * uv; }
;                 u32x4 w; w.x = cvt_pk_bf16(o[0], o[1]); w.y = cvt_pk_bf16(o[2], o[3]); w.z = cvt_pk_bf16(o[4], o[5]); w.w = cvt_pk_bf16(o[6], o[7]);
;                 *(u32x4*)(H + (size_t)row * FF + col0) = w;
	v_fmamk_f32 v96, v230, 0x3a800000, v158
	v_rsq_f32_e32 v96, v96
	s_nop 0
	v_pk_mul_f32 v[92:93], v[92:93], v[96:97] op_sel_hi:[1,0]
	v_pk_mul_f32 v[94:95], v[94:95], v[96:97] op_sel_hi:[1,0]
	v_pk_mul_f32 v[88:89], v[88:89], v[96:97] op_sel_hi:[1,0]
	v_pk_mul_f32 v[90:91], v[90:91], v[96:97] op_sel_hi:[1,0]
	v_pk_mul_f32 v[84:85], v[84:85], v[96:97] op_sel_hi:[1,0]
	v_pk_mul_f32 v[86:87], v[86:87], v[96:97] op_sel_hi:[1,0]
	v_pk_mul_f32 v[80:81], v[80:81], v[96:97] op_sel_hi:[1,0]
	v_pk_mul_f32 v[82:83], v[82:83], v[96:97] op_sel_hi:[1,0]
	v_mul_f32_e32 v96, 0xbfb8aa3b, v92
	v_mul_f32_e32 v97, 0xbfb8aa3b, v93
	v_mul_f32_e32 v100, 0xbfb8aa3b, v94
	v_mul_f32_e32 v101, 0xbfb8aa3b, v95
	v_mul_f32_e32 v102, 0xbfb8aa3b, v88
	v_mul_f32_e32 v103, 0xbfb8aa3b, v89
	v_mul_f32_e32 v104, 0xbfb8aa3b, v90
	v_mul_f32_e32 v105, 0xbfb8aa3b, v91
	v_exp_f32_e32 v96, v96
	v_exp_f32_e32 v97, v97
	v_exp_f32_e32 v100, v100
	v_exp_f32_e32 v101, v101
	v_exp_f32_e32 v102, v102
	v_exp_f32_e32 v103, v103
	v_exp_f32_e32 v104, v104
	v_exp_f32_e32 v105, v105
	v_add_f32_e32 v96, 1.0, v96
	v_add_f32_e32 v97, 1.0, v97
	v_add_f32_e32 v100, 1.0, v100
	v_add_f32_e32 v101, 1.0, v101
	v_add_f32_e32 v102, 1.0, v102
	v_add_f32_e32 v103, 1.0, v103
	v_add_f32_e32 v104, 1.0, v104
	v_add_f32_e32 v105, 1.0, v105
	v_rcp_f32_e32 v96, v96
	v_rcp_f32_e32 v97, v97
	v_rcp_f32_e32 v100, v100
	v_rcp_f32_e32 v101, v101
	v_rcp_f32_e32 v102, v102
	v_rcp_f32_e32 v103, v103
	v_rcp_f32_e32 v104, v104
	v_rcp_f32_e32 v105, v105
	v_pk_mul_f32 v[92:93], v[92:93], v[96:97]
	v_pk_mul_f32 v[94:95], v[94:95], v[100:101]
	v_pk_mul_f32 v[88:89], v[88:89], v[102:103]
	v_pk_mul_f32 v[90:91], v[90:91], v[104:105]
	v_pk_mul_f32 v[84:85], v[84:85], v[92:93]
	v_pk_mul_f32 v[86:87], v[86:87], v[94:95]
	v_pk_mul_f32 v[88:89], v[80:81], v[88:89]
	v_pk_mul_f32 v[90:91], v[82:83], v[90:91]
	v_cvt_pk_bf16_f32 v80, v84, v85
	v_cvt_pk_bf16_f32 v81, v86, v87
	v_cvt_pk_bf16_f32 v82, v88, v89
	v_cvt_pk_bf16_f32 v83, v90, v91
	global_store_dwordx4 v[98:99], v[80:83], off
	s_nop 0
	s_nop 0
	v_or_b32_e32 v81, 48, v144
	v_mad_i64_i32 v[82:83], s[6:7], v81, s33, v[146:147]
	v_lshl_add_u64 v[82:83], v[82:83], 0, v[148:149]
	s_waitcnt vmcnt(7)
	v_fmamk_f32 v80, v231, 0x3a800000, v158
	v_rsq_f32_e32 v80, v80
	s_nop 0
	v_pk_mul_f32 v[76:77], v[76:77], v[80:81] op_sel_hi:[1,0]
	v_pk_mul_f32 v[78:79], v[78:79], v[80:81] op_sel_hi:[1,0]
	v_pk_mul_f32 v[72:73], v[72:73], v[80:81] op_sel_hi:[1,0]
	v_pk_mul_f32 v[74:75], v[74:75], v[80:81] op_sel_hi:[1,0]
	v_pk_mul_f32 v[68:69], v[68:69], v[80:81] op_sel_hi:[1,0]
	v_pk_mul_f32 v[70:71], v[70:71], v[80:81] op_sel_hi:[1,0]
	v_pk_mul_f32 v[64:65], v[64:65], v[80:81] op_sel_hi:[1,0]
	v_pk_mul_f32 v[66:67], v[66:67], v[80:81] op_sel_hi:[1,0]
	v_mul_f32_e32 v80, 0xbfb8aa3b, v76
	v_mul_f32_e32 v81, 0xbfb8aa3b, v77
	v_mul_f32_e32 v84, 0xbfb8aa3b, v78
	v_mul_f32_e32 v85, 0xbfb8aa3b, v79
	v_mul_f32_e32 v86, 0xbfb8aa3b, v72
	v_mul_f32_e32 v87, 0xbfb8aa3b, v73
	v_mul_f32_e32 v88, 0xbfb8aa3b, v74
	v_mul_f32_e32 v89, 0xbfb8aa3b, v75
	v_exp_f32_e32 v80, v80
	v_exp_f32_e32 v81, v81
	v_exp_f32_e32 v84, v84
	v_exp_f32_e32 v85, v85
	v_exp_f32_e32 v86, v86
	v_exp_f32_e32 v87, v87
	v_exp_f32_e32 v88, v88
	v_exp_f32_e32 v89, v89
	v_add_f32_e32 v80, 1.0, v80
	v_add_f32_e32 v81, 1.0, v81
	v_add_f32_e32 v84, 1.0, v84
	v_add_f32_e32 v85, 1.0, v85
	v_add_f32_e32 v86, 1.0, v86
	v_add_f32_e32 v87, 1.0, v87
	v_add_f32_e32 v88, 1.0, v88
	v_add_f32_e32 v89, 1.0, v89
	v_rcp_f32_e32 v80, v80
	v_rcp_f32_e32 v81, v81
	v_rcp_f32_e32 v84, v84
	v_rcp_f32_e32 v85, v85
	v_rcp_f32_e32 v86, v86
	v_rcp_f32_e32 v87, v87
	v_rcp_f32_e32 v88, v88
	v_rcp_f32_e32 v89, v89
	v_pk_mul_f32 v[76:77], v[76:77], v[80:81]
	v_pk_mul_f32 v[78:79], v[78:79], v[84:85]
	v_pk_mul_f32 v[72:73], v[72:73], v[86:87]
	v_pk_mul_f32 v[74:75], v[74:75], v[88:89]
	v_pk_mul_f32 v[68:69], v[68:69], v[76:77]
	v_pk_mul_f32 v[70:71], v[70:71], v[78:79]
	v_pk_mul_f32 v[72:73], v[64:65], v[72:73]
	v_pk_mul_f32 v[74:75], v[66:67], v[74:75]
	v_cvt_pk_bf16_f32 v64, v68, v69
	v_cvt_pk_bf16_f32 v65, v70, v71
	v_cvt_pk_bf16_f32 v66, v72, v73
	v_cvt_pk_bf16_f32 v67, v74, v75
	global_store_dwordx4 v[82:83], v[64:67], off
	s_nop 0
	s_nop 0
	v_add_u32_e32 v65, 0x80, v144
	v_mad_i64_i32 v[66:67], s[6:7], v65, s33, v[146:147]
	v_lshl_add_u64 v[66:67], v[66:67], 0, v[148:149]
	s_waitcnt vmcnt(7)
	v_fmamk_f32 v64, v232, 0x3a800000, v158
	v_rsq_f32_e32 v64, v64
	s_nop 0
	v_pk_mul_f32 v[60:61], v[60:61], v[64:65] op_sel_hi:[1,0]
	v_pk_mul_f32 v[62:63], v[62:63], v[64:65] op_sel_hi:[1,0]
	v_pk_mul_f32 v[56:57], v[56:57], v[64:65] op_sel_hi:[1,0]
	v_pk_mul_f32 v[58:59], v[58:59], v[64:65] op_sel_hi:[1,0]
	v_pk_mul_f32 v[52:53], v[52:53], v[64:65] op_sel_hi:[1,0]
	v_pk_mul_f32 v[54:55], v[54:55], v[64:65] op_sel_hi:[1,0]
	v_pk_mul_f32 v[48:49], v[48:49], v[64:65] op_sel_hi:[1,0]
	v_pk_mul_f32 v[50:51], v[50:51], v[64:65] op_sel_hi:[1,0]
	v_mul_f32_e32 v64, 0xbfb8aa3b, v60
	v_mul_f32_e32 v65, 0xbfb8aa3b, v61
	v_mul_f32_e32 v68, 0xbfb8aa3b, v62
	v_mul_f32_e32 v69, 0xbfb8aa3b, v63
	v_mul_f32_e32 v70, 0xbfb8aa3b, v56
	v_mul_f32_e32 v71, 0xbfb8aa3b, v57
	v_mul_f32_e32 v72, 0xbfb8aa3b, v58
	v_mul_f32_e32 v73, 0xbfb8aa3b, v59
	v_exp_f32_e32 v64, v64
	v_exp_f32_e32 v65, v65
	v_exp_f32_e32 v68, v68
	v_exp_f32_e32 v69, v69
	v_exp_f32_e32 v70, v70
	v_exp_f32_e32 v71, v71
	v_exp_f32_e32 v72, v72
	v_exp_f32_e32 v73, v73
	v_add_f32_e32 v64, 1.0, v64
	v_add_f32_e32 v65, 1.0, v65
	v_add_f32_e32 v68, 1.0, v68
	v_add_f32_e32 v69, 1.0, v69
	v_add_f32_e32 v70, 1.0, v70
	v_add_f32_e32 v71, 1.0, v71
	v_add_f32_e32 v72, 1.0, v72
	v_add_f32_e32 v73, 1.0, v73
	v_rcp_f32_e32 v64, v64
	v_rcp_f32_e32 v65, v65
	v_rcp_f32_e32 v68, v68
	v_rcp_f32_e32 v69, v69
	v_rcp_f32_e32 v70, v70
	v_rcp_f32_e32 v71, v71
	v_rcp_f32_e32 v72, v72
	v_rcp_f32_e32 v73, v73
	v_pk_mul_f32 v[60:61], v[60:61], v[64:65]
	v_pk_mul_f32 v[62:63], v[62:63], v[68:69]
	v_pk_mul_f32 v[56:57], v[56:57], v[70:71]
	v_pk_mul_f32 v[58:59], v[58:59], v[72:73]
	v_pk_mul_f32 v[52:53], v[52:53], v[60:61]
	v_pk_mul_f32 v[54:55], v[54:55], v[62:63]
	v_pk_mul_f32 v[56:57], v[48:49], v[56:57]
	v_pk_mul_f32 v[58:59], v[50:51], v[58:59]
	v_cvt_pk_bf16_f32 v48, v52, v53
	v_cvt_pk_bf16_f32 v49, v54, v55
	v_cvt_pk_bf16_f32 v50, v56, v57
	v_cvt_pk_bf16_f32 v51, v58, v59
	global_store_dwordx4 v[66:67], v[48:51], off
	s_nop 0
	s_nop 0
	v_add_u32_e32 v49, 0x90, v144
	v_mad_i64_i32 v[50:51], s[6:7], v49, s33, v[146:147]
	v_lshl_add_u64 v[50:51], v[50:51], 0, v[148:149]
	s_waitcnt vmcnt(7)
; __device__ __forceinline__ unsigned cvt_pk_bf16(float lo, float hi) { f32x2_t v = {lo, hi}; bf16x2_t b = __builtin_convertvector(v, bf16x2_t); return __builtin_bit_cast(unsigned, b); }
; __device__ __forceinline__ float rstd_of(const float* ss, int row) { return __builtin_amdgcn_rsqf(ss[row] * (1.0f / 1024.0f) + RMS_EPS); }
; __device__ __forceinline__ float sigmoidf_(float v) { return __builtin_amdgcn_rcpf(1.0f + __builtin_amdgcn_exp2f(-v * LOG2E)); }
; #define PG8_BAR __builtin_amdgcn_s_barrier()
; template <class Epi>
; __device__ __forceinline__ void gemm_phase(LAS unsigned char* lds, const Gemm g, const StaticOrder& S, const Epi& E) {
;     ...
;         if (wr == 0) PG8_BAR;
;         E(acc, cur, wr, wc, fr, fq);
;         if (!has_next) break;
; #pragma unroll
;         for (int a = 0; a < 2; ++a)
; #pragma unroll
;             for (int b = 0; b < 2; ++b)
; #pragma unroll
;                 for (int m = 0; m < 4; ++m)
; #pragma unroll
;                     for (int n = 0; n < 2; ++n) acc[a][b][m][n] = (f32x4){0.f, 0.f, 0.f, 0.f};
;         cur = nxt; cA = nA; cB = nB; ++ui;
;         if (wr == 1) PG8_BAR;
;     __device__ __forceinline__ void operator()(const Acc& acc, const Unit& u, int wr, int wc, int fr, int fq) const {
;     ...
;             for (int m = 0; m < 4; ++m) {
;                 const int row = row0 + ai * HALF + m * 16; const float rs = rstd_of(ss, row);
;                 float o[8];
; #pragma unroll
;                 for (int n = 0; n < 2; ++n)
; #pragma unroll
;                     for (int e = 0; e < 4; ++e) { const float gv = acc[ai][0][m][n][e] * rs, uv = acc[ai][1][m][n][e] * rs; o[4 * n + e] = gv * sigmoidf_(gv) * uv; }
;                 u32x4 w; w.x = cvt_pk_bf16(o[0], o[1]); w.y = cvt_pk_bf16(o[2], o[3]); w.z = cvt_pk_bf16(o[4], o[5]); w.w = cvt_pk_bf16(o[6], o[7]);
;                 *(u32x4*)(H + (size_t)row * FF + col0) = w;
;             }
	v_fmamk_f32 v48, v233, 0x3a800000, v158
	v_rsq_f32_e32 v48, v48
	s_nop 0
	v_pk_mul_f32 v[44:45], v[44:45], v[48:49] op_sel_hi:[1,0]
	v_pk_mul_f32 v[46:47], v[46:47], v[48:49] op_sel_hi:[1,0]
	v_pk_mul_f32 v[40:41], v[40:41], v[48:49] op_sel_hi:[1,0]
	v_pk_mul_f32 v[42:43], v[42:43], v[48:49] op_sel_hi:[1,0]
	v_pk_mul_f32 v[36:37], v[36:37], v[48:49] op_sel_hi:[1,0]
	v_pk_mul_f32 v[38:39], v[38:39], v[48:49] op_sel_hi:[1,0]
	v_pk_mul_f32 v[32:33], v[32:33], v[48:49] op_sel_hi:[1,0]
	v_pk_mul_f32 v[34:35], v[34:35], v[48:49] op_sel_hi:[1,0]
	v_mul_f32_e32 v48, 0xbfb8aa3b, v44
	v_mul_f32_e32 v49, 0xbfb8aa3b, v45
	v_mul_f32_e32 v52, 0xbfb8aa3b, v46
	v_mul_f32_e32 v53, 0xbfb8aa3b, v47
	v_mul_f32_e32 v54, 0xbfb8aa3b, v40
	v_mul_f32_e32 v55, 0xbfb8aa3b, v41
	v_mul_f32_e32 v56, 0xbfb8aa3b, v42
	v_mul_f32_e32 v57, 0xbfb8aa3b, v43
	v_exp_f32_e32 v48, v48
	v_exp_f32_e32 v49, v49
	v_exp_f32_e32 v52, v52
	v_exp_f32_e32 v53, v53
	v_exp_f32_e32 v54, v54
	v_exp_f32_e32 v55, v55
	v_exp_f32_e32 v56, v56
	v_exp_f32_e32 v57, v57
	v_add_f32_e32 v48, 1.0, v48
	v_add_f32_e32 v49, 1.0, v49
	v_add_f32_e32 v52, 1.0, v52
	v_add_f32_e32 v53, 1.0, v53
	v_add_f32_e32 v54, 1.0, v54
	v_add_f32_e32 v55, 1.0, v55
	v_add_f32_e32 v56, 1.0, v56
	v_add_f32_e32 v57, 1.0, v57
	v_rcp_f32_e32 v48, v48
	v_rcp_f32_e32 v49, v49
	v_rcp_f32_e32 v52, v52
	v_rcp_f32_e32 v53, v53
	v_rcp_f32_e32 v54, v54
	v_rcp_f32_e32 v55, v55
	v_rcp_f32_e32 v56, v56
	v_rcp_f32_e32 v57, v57
	v_pk_mul_f32 v[44:45], v[44:45], v[48:49]
	v_pk_mul_f32 v[46:47], v[46:47], v[52:53]
	v_pk_mul_f32 v[40:41], v[40:41], v[54:55]
	v_pk_mul_f32 v[42:43], v[42:43], v[56:57]
	v_pk_mul_f32 v[36:37], v[36:37], v[44:45]
	v_pk_mul_f32 v[38:39], v[38:39], v[46:47]
	v_pk_mul_f32 v[40:41], v[32:33], v[40:41]
	v_pk_mul_f32 v[42:43], v[34:35], v[42:43]
	v_cvt_pk_bf16_f32 v32, v36, v37
	v_cvt_pk_bf16_f32 v33, v38, v39
	v_cvt_pk_bf16_f32 v34, v40, v41
	v_cvt_pk_bf16_f32 v35, v42, v43
	global_store_dwordx4 v[50:51], v[32:35], off
	s_nop 0
	s_nop 0
	v_add_u32_e32 v33, 0xa0, v144
	v_mad_i64_i32 v[34:35], s[6:7], v33, s33, v[146:147]
	v_lshl_add_u64 v[34:35], v[34:35], 0, v[148:149]
	s_waitcnt vmcnt(7)
	v_fmamk_f32 v32, v234, 0x3a800000, v158
	v_rsq_f32_e32 v32, v32
	s_nop 0
	v_pk_mul_f32 v[28:29], v[28:29], v[32:33] op_sel_hi:[1,0]
	v_pk_mul_f32 v[30:31], v[30:31], v[32:33] op_sel_hi:[1,0]
	v_pk_mul_f32 v[24:25], v[24:25], v[32:33] op_sel_hi:[1,0]
	v_pk_mul_f32 v[26:27], v[26:27], v[32:33] op_sel_hi:[1,0]
	v_pk_mul_f32 v[20:21], v[20:21], v[32:33] op_sel_hi:[1,0]
	v_pk_mul_f32 v[22:23], v[22:23], v[32:33] op_sel_hi:[1,0]
	v_pk_mul_f32 v[16:17], v[16:17], v[32:33] op_sel_hi:[1,0]
	v_pk_mul_f32 v[18:19], v[18:19], v[32:33] op_sel_hi:[1,0]
	v_mul_f32_e32 v32, 0xbfb8aa3b, v28
	v_mul_f32_e32 v33, 0xbfb8aa3b, v29
	v_mul_f32_e32 v36, 0xbfb8aa3b, v30
	v_mul_f32_e32 v37, 0xbfb8aa3b, v31
	v_mul_f32_e32 v38, 0xbfb8aa3b, v24
	v_mul_f32_e32 v39, 0xbfb8aa3b, v25
	v_mul_f32_e32 v40, 0xbfb8aa3b, v26
	v_mul_f32_e32 v41, 0xbfb8aa3b, v27
	v_exp_f32_e32 v32, v32
	v_exp_f32_e32 v33, v33
	v_exp_f32_e32 v36, v36
	v_exp_f32_e32 v37, v37
	v_exp_f32_e32 v38, v38
	v_exp_f32_e32 v39, v39
	v_exp_f32_e32 v40, v40
	v_exp_f32_e32 v41, v41
	v_add_f32_e32 v32, 1.0, v32
	v_add_f32_e32 v33, 1.0, v33
	v_add_f32_e32 v36, 1.0, v36
	v_add_f32_e32 v37, 1.0, v37
	v_add_f32_e32 v38, 1.0, v38
	v_add_f32_e32 v39, 1.0, v39
	v_add_f32_e32 v40, 1.0, v40
	v_add_f32_e32 v41, 1.0, v41
	v_rcp_f32_e32 v32, v32
	v_rcp_f32_e32 v33, v33
	v_rcp_f32_e32 v36, v36
	v_rcp_f32_e32 v37, v37
	v_rcp_f32_e32 v38, v38
	v_rcp_f32_e32 v39, v39
	v_rcp_f32_e32 v40, v40
	v_rcp_f32_e32 v41, v41
	v_pk_mul_f32 v[28:29], v[28:29], v[32:33]
	v_pk_mul_f32 v[30:31], v[30:31], v[36:37]
	v_pk_mul_f32 v[24:25], v[24:25], v[38:39]
	v_pk_mul_f32 v[26:27], v[26:27], v[40:41]
	v_pk_mul_f32 v[20:21], v[20:21], v[28:29]
	v_pk_mul_f32 v[22:23], v[22:23], v[30:31]
	v_pk_mul_f32 v[24:25], v[16:17], v[24:25]
	v_pk_mul_f32 v[26:27], v[18:19], v[26:27]
	v_cvt_pk_bf16_f32 v16, v20, v21
	v_cvt_pk_bf16_f32 v17, v22, v23
	v_cvt_pk_bf16_f32 v18, v24, v25
	v_cvt_pk_bf16_f32 v19, v26, v27
	global_store_dwordx4 v[34:35], v[16:19], off
	s_nop 0
	s_nop 0
	v_add_u32_e32 v17, 0xb0, v144
	v_mad_i64_i32 v[18:19], s[6:7], v17, s33, v[146:147]
	v_lshl_add_u64 v[18:19], v[18:19], 0, v[148:149]
	s_waitcnt vmcnt(7)
	v_fmamk_f32 v16, v235, 0x3a800000, v158
	v_rsq_f32_e32 v16, v16
	s_nop 0
	v_pk_mul_f32 v[12:13], v[12:13], v[16:17] op_sel_hi:[1,0]
	v_pk_mul_f32 v[14:15], v[14:15], v[16:17] op_sel_hi:[1,0]
	v_pk_mul_f32 v[8:9], v[8:9], v[16:17] op_sel_hi:[1,0]
	v_pk_mul_f32 v[10:11], v[10:11], v[16:17] op_sel_hi:[1,0]
	v_pk_mul_f32 v[4:5], v[4:5], v[16:17] op_sel_hi:[1,0]
	v_pk_mul_f32 v[6:7], v[6:7], v[16:17] op_sel_hi:[1,0]
	v_pk_mul_f32 v[0:1], v[0:1], v[16:17] op_sel_hi:[1,0]
	v_pk_mul_f32 v[2:3], v[2:3], v[16:17] op_sel_hi:[1,0]
	v_mul_f32_e32 v16, 0xbfb8aa3b, v12
	v_mul_f32_e32 v17, 0xbfb8aa3b, v13
	v_mul_f32_e32 v20, 0xbfb8aa3b, v14
	v_mul_f32_e32 v21, 0xbfb8aa3b, v15
	v_mul_f32_e32 v22, 0xbfb8aa3b, v8
	v_mul_f32_e32 v23, 0xbfb8aa3b, v9
	v_mul_f32_e32 v24, 0xbfb8aa3b, v10
	v_mul_f32_e32 v25, 0xbfb8aa3b, v11
	v_exp_f32_e32 v16, v16
	v_exp_f32_e32 v17, v17
	v_exp_f32_e32 v20, v20
	v_exp_f32_e32 v21, v21
	v_exp_f32_e32 v22, v22
	v_exp_f32_e32 v23, v23
	v_exp_f32_e32 v24, v24
	v_exp_f32_e32 v25, v25
	v_add_f32_e32 v16, 1.0, v16
	v_add_f32_e32 v17, 1.0, v17
	v_add_f32_e32 v20, 1.0, v20
	v_add_f32_e32 v21, 1.0, v21
	v_add_f32_e32 v22, 1.0, v22
	v_add_f32_e32 v23, 1.0, v23
	v_add_f32_e32 v24, 1.0, v24
	v_add_f32_e32 v25, 1.0, v25
	v_rcp_f32_e32 v16, v16
	v_rcp_f32_e32 v17, v17
	v_rcp_f32_e32 v20, v20
	v_rcp_f32_e32 v21, v21
	v_rcp_f32_e32 v22, v22
	v_rcp_f32_e32 v23, v23
	v_rcp_f32_e32 v24, v24
	v_rcp_f32_e32 v25, v25
	v_pk_mul_f32 v[12:13], v[12:13], v[16:17]
	v_pk_mul_f32 v[14:15], v[14:15], v[20:21]
	v_pk_mul_f32 v[8:9], v[8:9], v[22:23]
	v_pk_mul_f32 v[10:11], v[10:11], v[24:25]
	v_pk_mul_f32 v[4:5], v[4:5], v[12:13]
	v_pk_mul_f32 v[6:7], v[6:7], v[14:15]
	v_pk_mul_f32 v[8:9], v[0:1], v[8:9]
	v_pk_mul_f32 v[10:11], v[2:3], v[10:11]
	v_cvt_pk_bf16_f32 v0, v4, v5
	v_cvt_pk_bf16_f32 v1, v6, v7
	v_cvt_pk_bf16_f32 v2, v8, v9
	v_cvt_pk_bf16_f32 v3, v10, v11
	global_store_dwordx4 v[18:19], v[0:3], off
	s_cbranch_vccnz .LBB0_210
	s_andn2_b64 vcc, exec, s[0:1]
	s_cbranch_vccnz .LBB0_209
	s_barrier
	s_branch .LBB0_209

; __device__ __forceinline__ unsigned cvt_pk_bf16(float lo, float hi) { f32x2_t v = {lo, hi}; bf16x2_t b = __builtin_convertvector(v, bf16x2_t); return __builtin_bit_cast(unsigned, b); }
; __device__ __forceinline__ float rstd_of(const float* ss, int row) { return __builtin_amdgcn_rsqf(ss[row] * (1.0f / 1024.0f) + RMS_EPS); }
; __device__ __forceinline__ float sigmoidf_(float v) { return __builtin_amdgcn_rcpf(1.0f + __builtin_amdgcn_exp2f(-v * LOG2E)); }
;     __device__ __forceinline__ void operator()(const Acc& acc, const Unit& u, int wr, int wc, int fr, int fq) const {
;         const int row0 = u.pm * BM + wr * 64 + fr, col0 = u.pn * 128 + wc * 32 + 8 * fq;
; #pragma unroll
;         for (int ai = 0; ai < 2; ++ai)
; #pragma unroll
;             for (int m = 0; m < 4; ++m) {
;                 const int row = row0 + ai * HALF + m * 16; const float rs = rstd_of(ss, row);
;                 float o[8];
; #pragma unroll
;                 for (int n = 0; n < 2; ++n)
; #pragma unroll
;                     for (int e = 0; e < 4; ++e) { const float gv = acc[ai][0][m][n][e] * rs, uv = acc[ai][1][m][n][e] * rs; o[4 * n + e] = gv * sigmoidf_(gv) * uv; }
;                 u32x4 w; w.x = cvt_pk_bf16(o[0], o[1]); w.y = cvt_pk_bf16(o[2], o[3]); w.z = cvt_pk_bf16(o[4], o[5]); w.w = cvt_pk_bf16(o[6], o[7]);
;                 *(u32x4*)(H + (size_t)row * FF + col0) = w;
.LBB0_1353:
	v_lshl_add_u32 v144, s36, 8, v152
	v_ashrrev_i32_e32 v145, 31, v144
	v_lshl_add_u64 v[150:151], v[144:145], 2, s[2:3]
	global_load_dword v228, v[150:151], off
	global_load_dword v229, v[150:151], off offset:64
	global_load_dword v230, v[150:151], off offset:128
	global_load_dword v231, v[150:151], off offset:192
	global_load_dword v232, v[150:151], off offset:512
	global_load_dword v233, v[150:151], off offset:576
	global_load_dword v234, v[150:151], off offset:640
	global_load_dword v235, v[150:151], off offset:704
	v_or_b32_e32 v164, 16, v144
	v_ashrrev_i32_e32 v165, 31, v164
	v_lshl_add_u64 v[166:167], v[164:165], 2, s[2:3]
	v_lshl_or_b32 v148, s37, 7, v154
	v_mov_b64_e32 v[146:147], s[20:21]
	v_ashrrev_i32_e32 v149, 31, v148
	v_mad_i64_i32 v[162:163], s[36:37], v144, s33, v[146:147]
	v_lshlrev_b64 v[148:149], 1, v[148:149]
	v_lshl_add_u64 v[162:163], v[162:163], 0, v[148:149]
	v_readlane_b32 s48, v255, 6
	s_andn2_b64 vcc, exec, s[6:7]
	s_mov_b64 s[6:7], -1
	v_readlane_b32 s49, v255, 7
	v_readlane_b32 s50, v255, 8
	v_readlane_b32 s51, v255, 9
	s_waitcnt vmcnt(7)
	v_fmamk_f32 v145, v228, 0x3a800000, v158
	v_rsq_f32_e32 v160, v145
	s_nop 0
	v_pk_mul_f32 v[124:125], v[124:125], v[160:161] op_sel_hi:[1,0]
	v_pk_mul_f32 v[126:127], v[126:127], v[160:161] op_sel_hi:[1,0]
	v_pk_mul_f32 v[120:121], v[120:121], v[160:161] op_sel_hi:[1,0]
	v_pk_mul_f32 v[122:123], v[122:123], v[160:161] op_sel_hi:[1,0]
	v_pk_mul_f32 v[116:117], v[116:117], v[160:161] op_sel_hi:[1,0]
	v_pk_mul_f32 v[118:119], v[118:119], v[160:161] op_sel_hi:[1,0]
	v_pk_mul_f32 v[112:113], v[112:113], v[160:161] op_sel_hi:[1,0]
	v_pk_mul_f32 v[114:115], v[114:115], v[160:161] op_sel_hi:[1,0]
	v_mul_f32_e32 v145, 0xbfb8aa3b, v124
	v_mul_f32_e32 v159, 0xbfb8aa3b, v125
	v_mul_f32_e32 v160, 0xbfb8aa3b, v126
	v_mul_f32_e32 v165, 0xbfb8aa3b, v127
	v_mul_f32_e32 v168, 0xbfb8aa3b, v120
	v_mul_f32_e32 v169, 0xbfb8aa3b, v121
	v_mul_f32_e32 v170, 0xbfb8aa3b, v122
	v_mul_f32_e32 v171, 0xbfb8aa3b, v123
	v_exp_f32_e32 v145, v145
	v_exp_f32_e32 v159, v159
	v_exp_f32_e32 v160, v160
	v_exp_f32_e32 v165, v165
	v_exp_f32_e32 v168, v168
	v_exp_f32_e32 v169, v169
	v_exp_f32_e32 v170, v170
	v_exp_f32_e32 v171, v171
	v_add_f32_e32 v145, 1.0, v145
	v_add_f32_e32 v159, 1.0, v159
	v_add_f32_e32 v160, 1.0, v160
	v_add_f32_e32 v165, 1.0, v165
	v_add_f32_e32 v172, 1.0, v168
	v_add_f32_e32 v173, 1.0, v169
	v_add_f32_e32 v174, 1.0, v170
	v_add_f32_e32 v175, 1.0, v171
	v_rcp_f32_e32 v168, v145
	v_rcp_f32_e32 v169, v159
	v_rcp_f32_e32 v170, v160
	v_rcp_f32_e32 v171, v165
	v_rcp_f32_e32 v172, v172
	v_rcp_f32_e32 v173, v173
	v_rcp_f32_e32 v174, v174
	v_rcp_f32_e32 v175, v175
	v_pk_mul_f32 v[124:125], v[124:125], v[168:169]
	v_pk_mul_f32 v[126:127], v[126:127], v[170:171]
	v_pk_mul_f32 v[120:121], v[120:121], v[172:173]
	v_pk_mul_f32 v[122:123], v[122:123], v[174:175]
	v_pk_mul_f32 v[116:117], v[116:117], v[124:125]
	v_pk_mul_f32 v[118:119], v[118:119], v[126:127]
	v_pk_mul_f32 v[120:121], v[112:113], v[120:121]
	v_pk_mul_f32 v[122:123], v[114:115], v[122:123]
	v_cvt_pk_bf16_f32 v112, v116, v117
	v_cvt_pk_bf16_f32 v113, v118, v119
	v_cvt_pk_bf16_f32 v114, v120, v121
	v_cvt_pk_bf16_f32 v115, v122, v123
	global_store_dwordx4 v[162:163], v[112:115], off
	s_nop 0
	s_nop 0
	v_or_b32_e32 v112, 32, v144
	v_mad_i64_i32 v[114:115], s[36:37], v164, s33, v[146:147]
	v_lshl_add_u64 v[114:115], v[114:115], 0, v[148:149]
	s_waitcnt vmcnt(7)
	v_fmamk_f32 v113, v229, 0x3a800000, v158
	v_rsq_f32_e32 v116, v113
	v_ashrrev_i32_e32 v113, 31, v112
	v_lshl_add_u64 v[118:119], v[112:113], 2, s[2:3]
	v_pk_mul_f32 v[108:109], v[108:109], v[116:117] op_sel_hi:[1,0]
	v_pk_mul_f32 v[110:111], v[110:111], v[116:117] op_sel_hi:[1,0]
	v_pk_mul_f32 v[104:105], v[104:105], v[116:117] op_sel_hi:[1,0]
	v_pk_mul_f32 v[106:107], v[106:107], v[116:117] op_sel_hi:[1,0]
	v_pk_mul_f32 v[100:101], v[100:101], v[116:117] op_sel_hi:[1,0]
	v_pk_mul_f32 v[102:103], v[102:103], v[116:117] op_sel_hi:[1,0]
	v_pk_mul_f32 v[96:97], v[96:97], v[116:117] op_sel_hi:[1,0]
	v_pk_mul_f32 v[98:99], v[98:99], v[116:117] op_sel_hi:[1,0]
	v_mul_f32_e32 v113, 0xbfb8aa3b, v108
	v_mul_f32_e32 v116, 0xbfb8aa3b, v109
	v_mul_f32_e32 v117, 0xbfb8aa3b, v110
	v_mul_f32_e32 v120, 0xbfb8aa3b, v111
	v_mul_f32_e32 v121, 0xbfb8aa3b, v104
	v_mul_f32_e32 v122, 0xbfb8aa3b, v105
	v_mul_f32_e32 v123, 0xbfb8aa3b, v106
	v_mul_f32_e32 v124, 0xbfb8aa3b, v107
	v_exp_f32_e32 v113, v113
	v_exp_f32_e32 v116, v116
	v_exp_f32_e32 v117, v117
	v_exp_f32_e32 v120, v120
	v_exp_f32_e32 v121, v121
	v_exp_f32_e32 v122, v122
	v_exp_f32_e32 v123, v123
	v_exp_f32_e32 v124, v124
	v_add_f32_e32 v113, 1.0, v113
	v_add_f32_e32 v125, 1.0, v116
	v_add_f32_e32 v126, 1.0, v117
	v_add_f32_e32 v127, 1.0, v120
	v_add_f32_e32 v145, 1.0, v121
	v_add_f32_e32 v159, 1.0, v122
	v_add_f32_e32 v160, 1.0, v123
	v_add_f32_e32 v162, 1.0, v124
	v_rcp_f32_e32 v116, v113
	v_rcp_f32_e32 v117, v125
	v_rcp_f32_e32 v120, v126
	v_rcp_f32_e32 v121, v127
	v_rcp_f32_e32 v122, v145
	v_rcp_f32_e32 v123, v159
	v_rcp_f32_e32 v124, v160
	v_rcp_f32_e32 v125, v162
	v_pk_mul_f32 v[108:109], v[108:109], v[116:117]
	v_pk_mul_f32 v[110:111], v[110:111], v[120:121]
	v_pk_mul_f32 v[104:105], v[104:105], v[122:123]
	v_pk_mul_f32 v[106:107], v[106:107], v[124:125]
	v_pk_mul_f32 v[100:101], v[100:101], v[108:109]
	v_pk_mul_f32 v[102:103], v[102:103], v[110:111]
	v_pk_mul_f32 v[104:105], v[96:97], v[104:105]
	v_pk_mul_f32 v[106:107], v[98:99], v[106:107]
	v_cvt_pk_bf16_f32 v96, v100, v101
	v_cvt_pk_bf16_f32 v97, v102, v103
	v_cvt_pk_bf16_f32 v98, v104, v105
	v_cvt_pk_bf16_f32 v99, v106, v107
	global_store_dwordx4 v[114:115], v[96:99], off
	s_nop 0
	s_nop 0
	v_or_b32_e32 v96, 48, v144
	v_mad_i64_i32 v[98:99], s[36:37], v112, s33, v[146:147]
	v_lshl_add_u64 v[98:99], v[98:99], 0, v[148:149]
	s_waitcnt vmcnt(7)
; __device__ __forceinline__ unsigned cvt_pk_bf16(float lo, float hi) { f32x2_t v = {lo, hi}; bf16x2_t b = __builtin_convertvector(v, bf16x2_t); return __builtin_bit_cast(unsigned, b); }
; __device__ __forceinline__ float rstd_of(const float* ss, int row) { return __builtin_amdgcn_rsqf(ss[row] * (1.0f / 1024.0f) + RMS_EPS); }
; __device__ __forceinline__ float sigmoidf_(float v) { return __builtin_amdgcn_rcpf(1.0f + __builtin_amdgcn_exp2f(-v * LOG2E)); }
;     __device__ __forceinline__ void operator()(const Acc& acc, const Unit& u, int wr, int wc, int fr, int fq) const {
;     ...
;             for (int m = 0; m < 4; ++m) {
;                 const int row = row0 + ai * HALF + m * 16; const float rs = rstd_of(ss, row);
;                 float o[8];
; #pragma unroll
;                 for (int n = 0; n < 2; ++n)
; #pragma unroll
;                     for (int e = 0; e < 4; ++e) { const float gv = acc[ai][0][m][n][e] * rs, uv = acc[ai][1][m][n][e] * rs; o[4 * n + e] = gv * sigmoidf_(gv) * uv; }
;                 u32x4 w; w.x = cvt_pk_bf16(o[0], o[1]); w.y = cvt_pk_bf16(o[2], o[3]); w.z = cvt_pk_bf16(o[4], o[5]); w.w = cvt_pk_bf16(o[6], o[7]);
;                 *(u32x4*)(H + (size_t)row * FF + col0) = w;
	v_fmamk_f32 v97, v230, 0x3a800000, v158
	v_rsq_f32_e32 v100, v97
	v_ashrrev_i32_e32 v97, 31, v96
	v_lshl_add_u64 v[102:103], v[96:97], 2, s[2:3]
	v_pk_mul_f32 v[92:93], v[92:93], v[100:101] op_sel_hi:[1,0]
	v_pk_mul_f32 v[94:95], v[94:95], v[100:101] op_sel_hi:[1,0]
	v_pk_mul_f32 v[88:89], v[88:89], v[100:101] op_sel_hi:[1,0]
	v_pk_mul_f32 v[90:91], v[90:91], v[100:101] op_sel_hi:[1,0]
	v_pk_mul_f32 v[84:85], v[84:85], v[100:101] op_sel_hi:[1,0]
	v_pk_mul_f32 v[86:87], v[86:87], v[100:101] op_sel_hi:[1,0]
	v_pk_mul_f32 v[80:81], v[80:81], v[100:101] op_sel_hi:[1,0]
	v_pk_mul_f32 v[82:83], v[82:83], v[100:101] op_sel_hi:[1,0]
	v_mul_f32_e32 v97, 0xbfb8aa3b, v92
	v_mul_f32_e32 v100, 0xbfb8aa3b, v93
	v_mul_f32_e32 v101, 0xbfb8aa3b, v94
	v_mul_f32_e32 v104, 0xbfb8aa3b, v95
	v_mul_f32_e32 v105, 0xbfb8aa3b, v88
	v_mul_f32_e32 v106, 0xbfb8aa3b, v89
	v_mul_f32_e32 v107, 0xbfb8aa3b, v90
	v_mul_f32_e32 v108, 0xbfb8aa3b, v91
	v_exp_f32_e32 v97, v97
	v_exp_f32_e32 v100, v100
	v_exp_f32_e32 v101, v101
	v_exp_f32_e32 v104, v104
	v_exp_f32_e32 v105, v105
	v_exp_f32_e32 v106, v106
	v_exp_f32_e32 v107, v107
	v_exp_f32_e32 v108, v108
	v_add_f32_e32 v97, 1.0, v97
	v_add_f32_e32 v109, 1.0, v100
	v_add_f32_e32 v110, 1.0, v101
	v_add_f32_e32 v111, 1.0, v104
	v_add_f32_e32 v112, 1.0, v105
	v_add_f32_e32 v113, 1.0, v106
	v_add_f32_e32 v114, 1.0, v107
	v_add_f32_e32 v115, 1.0, v108
	v_rcp_f32_e32 v100, v97
	v_rcp_f32_e32 v101, v109
	v_rcp_f32_e32 v104, v110
	v_rcp_f32_e32 v105, v111
	v_rcp_f32_e32 v106, v112
	v_rcp_f32_e32 v107, v113
	v_rcp_f32_e32 v108, v114
	v_rcp_f32_e32 v109, v115
	v_pk_mul_f32 v[92:93], v[92:93], v[100:101]
	v_pk_mul_f32 v[94:95], v[94:95], v[104:105]
	v_pk_mul_f32 v[88:89], v[88:89], v[106:107]
	v_pk_mul_f32 v[90:91], v[90:91], v[108:109]
	v_pk_mul_f32 v[84:85], v[84:85], v[92:93]
	v_pk_mul_f32 v[86:87], v[86:87], v[94:95]
	v_pk_mul_f32 v[88:89], v[80:81], v[88:89]
	v_pk_mul_f32 v[90:91], v[82:83], v[90:91]
	v_cvt_pk_bf16_f32 v80, v84, v85
	v_cvt_pk_bf16_f32 v81, v86, v87
	v_cvt_pk_bf16_f32 v82, v88, v89
	v_cvt_pk_bf16_f32 v83, v90, v91
	global_store_dwordx4 v[98:99], v[80:83], off
	s_nop 0
	s_nop 0
	v_mad_i64_i32 v[82:83], s[36:37], v96, s33, v[146:147]
	v_lshl_add_u64 v[82:83], v[82:83], 0, v[148:149]
	s_waitcnt vmcnt(7)
	v_fmamk_f32 v80, v231, 0x3a800000, v158
	v_rsq_f32_e32 v80, v80
	s_nop 0
	v_pk_mul_f32 v[76:77], v[76:77], v[80:81] op_sel_hi:[1,0]
	v_pk_mul_f32 v[78:79], v[78:79], v[80:81] op_sel_hi:[1,0]
	v_pk_mul_f32 v[72:73], v[72:73], v[80:81] op_sel_hi:[1,0]
	v_pk_mul_f32 v[74:75], v[74:75], v[80:81] op_sel_hi:[1,0]
	v_pk_mul_f32 v[68:69], v[68:69], v[80:81] op_sel_hi:[1,0]
	v_pk_mul_f32 v[70:71], v[70:71], v[80:81] op_sel_hi:[1,0]
	v_pk_mul_f32 v[64:65], v[64:65], v[80:81] op_sel_hi:[1,0]
	v_pk_mul_f32 v[66:67], v[66:67], v[80:81] op_sel_hi:[1,0]
	v_mul_f32_e32 v80, 0xbfb8aa3b, v76
	v_mul_f32_e32 v81, 0xbfb8aa3b, v77
	v_mul_f32_e32 v84, 0xbfb8aa3b, v78
	v_mul_f32_e32 v85, 0xbfb8aa3b, v79
	v_mul_f32_e32 v86, 0xbfb8aa3b, v72
	v_mul_f32_e32 v87, 0xbfb8aa3b, v73
	v_mul_f32_e32 v88, 0xbfb8aa3b, v74
	v_mul_f32_e32 v89, 0xbfb8aa3b, v75
	v_exp_f32_e32 v80, v80
	v_exp_f32_e32 v81, v81
	v_exp_f32_e32 v84, v84
	v_exp_f32_e32 v85, v85
	v_exp_f32_e32 v86, v86
	v_exp_f32_e32 v87, v87
	v_exp_f32_e32 v88, v88
	v_exp_f32_e32 v89, v89
	v_add_f32_e32 v80, 1.0, v80
	v_add_f32_e32 v81, 1.0, v81
	v_add_f32_e32 v84, 1.0, v84
	v_add_f32_e32 v85, 1.0, v85
	v_add_f32_e32 v86, 1.0, v86
	v_add_f32_e32 v87, 1.0, v87
	v_add_f32_e32 v88, 1.0, v88
	v_add_f32_e32 v89, 1.0, v89
	v_rcp_f32_e32 v80, v80
	v_rcp_f32_e32 v81, v81
	v_rcp_f32_e32 v84, v84
	v_rcp_f32_e32 v85, v85
	v_rcp_f32_e32 v86, v86
	v_rcp_f32_e32 v87, v87
	v_rcp_f32_e32 v88, v88
	v_rcp_f32_e32 v89, v89
	v_pk_mul_f32 v[76:77], v[76:77], v[80:81]
	v_pk_mul_f32 v[78:79], v[78:79], v[84:85]
	v_pk_mul_f32 v[72:73], v[72:73], v[86:87]
	v_pk_mul_f32 v[74:75], v[74:75], v[88:89]
	v_pk_mul_f32 v[68:69], v[68:69], v[76:77]
	v_pk_mul_f32 v[70:71], v[70:71], v[78:79]
	v_pk_mul_f32 v[72:73], v[64:65], v[72:73]
	v_pk_mul_f32 v[74:75], v[66:67], v[74:75]
	v_cvt_pk_bf16_f32 v64, v68, v69
	v_cvt_pk_bf16_f32 v65, v70, v71
	v_cvt_pk_bf16_f32 v66, v72, v73
	v_cvt_pk_bf16_f32 v67, v74, v75
	global_store_dwordx4 v[82:83], v[64:67], off
	s_nop 0
	s_nop 0
	v_add_u32_e32 v65, 0x80, v144
	v_mad_i64_i32 v[66:67], s[36:37], v65, s33, v[146:147]
	v_lshl_add_u64 v[66:67], v[66:67], 0, v[148:149]
	s_waitcnt vmcnt(7)
	v_fmamk_f32 v64, v232, 0x3a800000, v158
	v_rsq_f32_e32 v64, v64
	s_nop 0
	v_pk_mul_f32 v[60:61], v[60:61], v[64:65] op_sel_hi:[1,0]
	v_pk_mul_f32 v[62:63], v[62:63], v[64:65] op_sel_hi:[1,0]
	v_pk_mul_f32 v[56:57], v[56:57], v[64:65] op_sel_hi:[1,0]
	v_pk_mul_f32 v[58:59], v[58:59], v[64:65] op_sel_hi:[1,0]
	v_pk_mul_f32 v[52:53], v[52:53], v[64:65] op_sel_hi:[1,0]
	v_pk_mul_f32 v[54:55], v[54:55], v[64:65] op_sel_hi:[1,0]
	v_pk_mul_f32 v[48:49], v[48:49], v[64:65] op_sel_hi:[1,0]
	v_pk_mul_f32 v[50:51], v[50:51], v[64:65] op_sel_hi:[1,0]
	v_mul_f32_e32 v64, 0xbfb8aa3b, v60
	v_mul_f32_e32 v65, 0xbfb8aa3b, v61
	v_mul_f32_e32 v68, 0xbfb8aa3b, v62
	v_mul_f32_e32 v69, 0xbfb8aa3b, v63
	v_mul_f32_e32 v70, 0xbfb8aa3b, v56
	v_mul_f32_e32 v71, 0xbfb8aa3b, v57
	v_mul_f32_e32 v72, 0xbfb8aa3b, v58
	v_mul_f32_e32 v73, 0xbfb8aa3b, v59
	v_exp_f32_e32 v64, v64
	v_exp_f32_e32 v65, v65
	v_exp_f32_e32 v68, v68
	v_exp_f32_e32 v69, v69
	v_exp_f32_e32 v70, v70
	v_exp_f32_e32 v71, v71
	v_exp_f32_e32 v72, v72
	v_exp_f32_e32 v73, v73
	v_add_f32_e32 v64, 1.0, v64
	v_add_f32_e32 v65, 1.0, v65
	v_add_f32_e32 v68, 1.0, v68
	v_add_f32_e32 v69, 1.0, v69
	v_add_f32_e32 v70, 1.0, v70
	v_add_f32_e32 v71, 1.0, v71
	v_add_f32_e32 v72, 1.0, v72
	v_add_f32_e32 v73, 1.0, v73
	v_rcp_f32_e32 v64, v64
	v_rcp_f32_e32 v65, v65
	v_rcp_f32_e32 v68, v68
	v_rcp_f32_e32 v69, v69
	v_rcp_f32_e32 v70, v70
	v_rcp_f32_e32 v71, v71
	v_rcp_f32_e32 v72, v72
	v_rcp_f32_e32 v73, v73
	v_pk_mul_f32 v[60:61], v[60:61], v[64:65]
	v_pk_mul_f32 v[62:63], v[62:63], v[68:69]
	v_pk_mul_f32 v[56:57], v[56:57], v[70:71]
	v_pk_mul_f32 v[58:59], v[58:59], v[72:73]
	v_pk_mul_f32 v[52:53], v[52:53], v[60:61]
	v_pk_mul_f32 v[54:55], v[54:55], v[62:63]
	v_pk_mul_f32 v[56:57], v[48:49], v[56:57]
	v_pk_mul_f32 v[58:59], v[50:51], v[58:59]
	v_cvt_pk_bf16_f32 v48, v52, v53
	v_cvt_pk_bf16_f32 v49, v54, v55
	v_cvt_pk_bf16_f32 v50, v56, v57
	v_cvt_pk_bf16_f32 v51, v58, v59
	global_store_dwordx4 v[66:67], v[48:51], off
	s_nop 0
	s_nop 0
	v_add_u32_e32 v49, 0x90, v144
	v_mad_i64_i32 v[50:51], s[36:37], v49, s33, v[146:147]
	v_lshl_add_u64 v[50:51], v[50:51], 0, v[148:149]
	s_waitcnt vmcnt(7)
; __device__ __forceinline__ unsigned cvt_pk_bf16(float lo, float hi) { f32x2_t v = {lo, hi}; bf16x2_t b = __builtin_convertvector(v, bf16x2_t); return __builtin_bit_cast(unsigned, b); }
; __device__ __forceinline__ float rstd_of(const float* ss, int row) { return __builtin_amdgcn_rsqf(ss[row] * (1.0f / 1024.0f) + RMS_EPS); }
; __device__ __forceinline__ float sigmoidf_(float v) { return __builtin_amdgcn_rcpf(1.0f + __builtin_amdgcn_exp2f(-v * LOG2E)); }
; #define PG8_BAR __builtin_amdgcn_s_barrier()
; template <class Epi>
; __device__ __forceinline__ void gemm_phase(LAS unsigned char* lds, const Gemm g, const StaticOrder& S, const Epi& E) {
;     ...
;         if (wr == 0) PG8_BAR;
;         E(acc, cur, wr, wc, fr, fq);
;         if (!has_next) break;
; #pragma unroll
;         for (int a = 0; a < 2; ++a)
; #pragma unroll
;             for (int b = 0; b < 2; ++b)
; #pragma unroll
;                 for (int m = 0; m < 4; ++m)
; #pragma unroll
;                     for (int n = 0; n < 2; ++n) acc[a][b][m][n] = (f32x4){0.f, 0.f, 0.f, 0.f};
;         cur = nxt; cA = nA; cB = nB; ++ui;
;         if (wr == 1) PG8_BAR;
;     __device__ __forceinline__ void operator()(const Acc& acc, const Unit& u, int wr, int wc, int fr, int fq) const {
;     ...
;             for (int m = 0; m < 4; ++m) {
;                 const int row = row0 + ai * HALF + m * 16; const float rs = rstd_of(ss, row);
;                 float o[8];
; #pragma unroll
;                 for (int n = 0; n < 2; ++n)
; #pragma unroll
;                     for (int e = 0; e < 4; ++e) { const float gv = acc[ai][0][m][n][e] * rs, uv = acc[ai][1][m][n][e] * rs; o[4 * n + e] = gv * sigmoidf_(gv) * uv; }
;                 u32x4 w; w.x = cvt_pk_bf16(o[0], o[1]); w.y = cvt_pk_bf16(o[2], o[3]); w.z = cvt_pk_bf16(o[4], o[5]); w.w = cvt_pk_bf16(o[6], o[7]);
;                 *(u32x4*)(H + (size_t)row * FF + col0) = w;
;             }
	v_fmamk_f32 v48, v233, 0x3a800000, v158
	v_rsq_f32_e32 v48, v48
	s_nop 0
	v_pk_mul_f32 v[44:45], v[44:45], v[48:49] op_sel_hi:[1,0]
	v_pk_mul_f32 v[46:47], v[46:47], v[48:49] op_sel_hi:[1,0]
	v_pk_mul_f32 v[40:41], v[40:41], v[48:49] op_sel_hi:[1,0]
	v_pk_mul_f32 v[42:43], v[42:43], v[48:49] op_sel_hi:[1,0]
	v_pk_mul_f32 v[36:37], v[36:37], v[48:49] op_sel_hi:[1,0]
	v_pk_mul_f32 v[38:39], v[38:39], v[48:49] op_sel_hi:[1,0]
	v_pk_mul_f32 v[32:33], v[32:33], v[48:49] op_sel_hi:[1,0]
	v_pk_mul_f32 v[34:35], v[34:35], v[48:49] op_sel_hi:[1,0]
	v_mul_f32_e32 v48, 0xbfb8aa3b, v44
	v_mul_f32_e32 v49, 0xbfb8aa3b, v45
	v_mul_f32_e32 v52, 0xbfb8aa3b, v46
	v_mul_f32_e32 v53, 0xbfb8aa3b, v47
	v_mul_f32_e32 v54, 0xbfb8aa3b, v40
	v_mul_f32_e32 v55, 0xbfb8aa3b, v41
	v_mul_f32_e32 v56, 0xbfb8aa3b, v42
	v_mul_f32_e32 v57, 0xbfb8aa3b, v43
	v_exp_f32_e32 v48, v48
	v_exp_f32_e32 v49, v49
	v_exp_f32_e32 v52, v52
	v_exp_f32_e32 v53, v53
	v_exp_f32_e32 v54, v54
	v_exp_f32_e32 v55, v55
	v_exp_f32_e32 v56, v56
	v_exp_f32_e32 v57, v57
	v_add_f32_e32 v48, 1.0, v48
	v_add_f32_e32 v49, 1.0, v49
	v_add_f32_e32 v52, 1.0, v52
	v_add_f32_e32 v53, 1.0, v53
	v_add_f32_e32 v54, 1.0, v54
	v_add_f32_e32 v55, 1.0, v55
	v_add_f32_e32 v56, 1.0, v56
	v_add_f32_e32 v57, 1.0, v57
	v_rcp_f32_e32 v48, v48
	v_rcp_f32_e32 v49, v49
	v_rcp_f32_e32 v52, v52
	v_rcp_f32_e32 v53, v53
	v_rcp_f32_e32 v54, v54
	v_rcp_f32_e32 v55, v55
	v_rcp_f32_e32 v56, v56
	v_rcp_f32_e32 v57, v57
	v_pk_mul_f32 v[44:45], v[44:45], v[48:49]
	v_pk_mul_f32 v[46:47], v[46:47], v[52:53]
	v_pk_mul_f32 v[40:41], v[40:41], v[54:55]
	v_pk_mul_f32 v[42:43], v[42:43], v[56:57]
	v_pk_mul_f32 v[36:37], v[36:37], v[44:45]
	v_pk_mul_f32 v[38:39], v[38:39], v[46:47]
	v_pk_mul_f32 v[40:41], v[32:33], v[40:41]
	v_pk_mul_f32 v[42:43], v[34:35], v[42:43]
	v_cvt_pk_bf16_f32 v32, v36, v37
	v_cvt_pk_bf16_f32 v33, v38, v39
	v_cvt_pk_bf16_f32 v34, v40, v41
	v_cvt_pk_bf16_f32 v35, v42, v43
	global_store_dwordx4 v[50:51], v[32:35], off
	s_nop 0
	s_nop 0
	v_add_u32_e32 v33, 0xa0, v144
	v_mad_i64_i32 v[34:35], s[36:37], v33, s33, v[146:147]
	v_lshl_add_u64 v[34:35], v[34:35], 0, v[148:149]
	s_waitcnt vmcnt(7)
	v_fmamk_f32 v32, v234, 0x3a800000, v158
	v_rsq_f32_e32 v32, v32
	s_nop 0
	v_pk_mul_f32 v[28:29], v[28:29], v[32:33] op_sel_hi:[1,0]
	v_pk_mul_f32 v[30:31], v[30:31], v[32:33] op_sel_hi:[1,0]
	v_pk_mul_f32 v[24:25], v[24:25], v[32:33] op_sel_hi:[1,0]
	v_pk_mul_f32 v[26:27], v[26:27], v[32:33] op_sel_hi:[1,0]
	v_pk_mul_f32 v[20:21], v[20:21], v[32:33] op_sel_hi:[1,0]
	v_pk_mul_f32 v[22:23], v[22:23], v[32:33] op_sel_hi:[1,0]
	v_pk_mul_f32 v[16:17], v[16:17], v[32:33] op_sel_hi:[1,0]
	v_pk_mul_f32 v[18:19], v[18:19], v[32:33] op_sel_hi:[1,0]
	v_mul_f32_e32 v32, 0xbfb8aa3b, v28
	v_mul_f32_e32 v33, 0xbfb8aa3b, v29
	v_mul_f32_e32 v36, 0xbfb8aa3b, v30
	v_mul_f32_e32 v37, 0xbfb8aa3b, v31
	v_mul_f32_e32 v38, 0xbfb8aa3b, v24
	v_mul_f32_e32 v39, 0xbfb8aa3b, v25
	v_mul_f32_e32 v40, 0xbfb8aa3b, v26
	v_mul_f32_e32 v41, 0xbfb8aa3b, v27
	v_exp_f32_e32 v32, v32
	v_exp_f32_e32 v33, v33
	v_exp_f32_e32 v36, v36
	v_exp_f32_e32 v37, v37
	v_exp_f32_e32 v38, v38
	v_exp_f32_e32 v39, v39
	v_exp_f32_e32 v40, v40
	v_exp_f32_e32 v41, v41
	v_add_f32_e32 v32, 1.0, v32
	v_add_f32_e32 v33, 1.0, v33
	v_add_f32_e32 v36, 1.0, v36
	v_add_f32_e32 v37, 1.0, v37
	v_add_f32_e32 v38, 1.0, v38
	v_add_f32_e32 v39, 1.0, v39
	v_add_f32_e32 v40, 1.0, v40
	v_add_f32_e32 v41, 1.0, v41
	v_rcp_f32_e32 v32, v32
	v_rcp_f32_e32 v33, v33
	v_rcp_f32_e32 v36, v36
	v_rcp_f32_e32 v37, v37
	v_rcp_f32_e32 v38, v38
	v_rcp_f32_e32 v39, v39
	v_rcp_f32_e32 v40, v40
	v_rcp_f32_e32 v41, v41
	v_pk_mul_f32 v[28:29], v[28:29], v[32:33]
	v_pk_mul_f32 v[30:31], v[30:31], v[36:37]
	v_pk_mul_f32 v[24:25], v[24:25], v[38:39]
	v_pk_mul_f32 v[26:27], v[26:27], v[40:41]
	v_pk_mul_f32 v[20:21], v[20:21], v[28:29]
	v_pk_mul_f32 v[22:23], v[22:23], v[30:31]
	v_pk_mul_f32 v[24:25], v[16:17], v[24:25]
	v_pk_mul_f32 v[26:27], v[18:19], v[26:27]
	v_cvt_pk_bf16_f32 v16, v20, v21
	v_cvt_pk_bf16_f32 v17, v22, v23
	v_cvt_pk_bf16_f32 v18, v24, v25
	v_cvt_pk_bf16_f32 v19, v26, v27
	global_store_dwordx4 v[34:35], v[16:19], off
	s_nop 0
	s_nop 0
	v_add_u32_e32 v17, 0xb0, v144
	v_mad_i64_i32 v[18:19], s[36:37], v17, s33, v[146:147]
	v_lshl_add_u64 v[18:19], v[18:19], 0, v[148:149]
	s_waitcnt vmcnt(7)
	v_fmamk_f32 v16, v235, 0x3a800000, v158
	v_rsq_f32_e32 v16, v16
	s_nop 0
	v_pk_mul_f32 v[12:13], v[12:13], v[16:17] op_sel_hi:[1,0]
	v_pk_mul_f32 v[14:15], v[14:15], v[16:17] op_sel_hi:[1,0]
	v_pk_mul_f32 v[8:9], v[8:9], v[16:17] op_sel_hi:[1,0]
	v_pk_mul_f32 v[10:11], v[10:11], v[16:17] op_sel_hi:[1,0]
	v_pk_mul_f32 v[4:5], v[4:5], v[16:17] op_sel_hi:[1,0]
	v_pk_mul_f32 v[6:7], v[6:7], v[16:17] op_sel_hi:[1,0]
	v_pk_mul_f32 v[0:1], v[0:1], v[16:17] op_sel_hi:[1,0]
	v_pk_mul_f32 v[2:3], v[2:3], v[16:17] op_sel_hi:[1,0]
	v_mul_f32_e32 v16, 0xbfb8aa3b, v12
	v_mul_f32_e32 v17, 0xbfb8aa3b, v13
	v_mul_f32_e32 v20, 0xbfb8aa3b, v14
	v_mul_f32_e32 v21, 0xbfb8aa3b, v15
	v_mul_f32_e32 v22, 0xbfb8aa3b, v8
	v_mul_f32_e32 v23, 0xbfb8aa3b, v9
	v_mul_f32_e32 v24, 0xbfb8aa3b, v10
	v_mul_f32_e32 v25, 0xbfb8aa3b, v11
	v_exp_f32_e32 v16, v16
	v_exp_f32_e32 v17, v17
	v_exp_f32_e32 v20, v20
	v_exp_f32_e32 v21, v21
	v_exp_f32_e32 v22, v22
	v_exp_f32_e32 v23, v23
	v_exp_f32_e32 v24, v24
	v_exp_f32_e32 v25, v25
	v_add_f32_e32 v16, 1.0, v16
	v_add_f32_e32 v17, 1.0, v17
	v_add_f32_e32 v20, 1.0, v20
	v_add_f32_e32 v21, 1.0, v21
	v_add_f32_e32 v22, 1.0, v22
	v_add_f32_e32 v23, 1.0, v23
	v_add_f32_e32 v24, 1.0, v24
	v_add_f32_e32 v25, 1.0, v25
	v_rcp_f32_e32 v16, v16
	v_rcp_f32_e32 v17, v17
	v_rcp_f32_e32 v20, v20
	v_rcp_f32_e32 v21, v21
	v_rcp_f32_e32 v22, v22
	v_rcp_f32_e32 v23, v23
	v_rcp_f32_e32 v24, v24
	v_rcp_f32_e32 v25, v25
	v_pk_mul_f32 v[12:13], v[12:13], v[16:17]
	v_pk_mul_f32 v[14:15], v[14:15], v[20:21]
	v_pk_mul_f32 v[8:9], v[8:9], v[22:23]
	v_pk_mul_f32 v[10:11], v[10:11], v[24:25]
	v_pk_mul_f32 v[4:5], v[4:5], v[12:13]
	v_pk_mul_f32 v[6:7], v[6:7], v[14:15]
	v_pk_mul_f32 v[8:9], v[0:1], v[8:9]
	v_pk_mul_f32 v[10:11], v[2:3], v[10:11]
	v_cvt_pk_bf16_f32 v0, v4, v5
	v_cvt_pk_bf16_f32 v1, v6, v7
	v_cvt_pk_bf16_f32 v2, v8, v9
	v_cvt_pk_bf16_f32 v3, v10, v11
	global_store_dwordx4 v[18:19], v[0:3], off
	s_cbranch_vccnz .LBB0_1346
	s_andn2_b64 vcc, exec, s[8:9]
	s_cbranch_vccnz .LBB0_1345
	s_barrier
	s_branch .LBB0_1345
